# adds post-phase RWKV group-norm loop with all 32 loads per 8 tokens issued before one wait, GLU weight fill with 4 loads in flight, S5 GLU pass-0 bias loads hoisted
# speedup vs baseline: 1.0333x; 1.0126x over previous
; DI void phase_post(const PRef& p, int l) {
;     ...
;   {
;     const uint4* g4 = reinterpret_cast<const uint4*>(glut);
;     uint4* l4 = reinterpret_cast<uint4*>(shm);
; #pragma unroll 4
;     for (int i = 0; i < 16; ++i) {
;       const int idx = tid + i * 512, row = idx >> 5, ch = idx & 31;
;       l4[row * 32 + (ch ^ (row & 15))] = g4[idx];
;     }
;   }
;   __syncthreads();
;   for (int item = blockIdx.x; item < NTOK / 128; item += gridDim.x) {
;     const int tk0 = item * 128;
;     {
;       const int c = tid & 255, half = tid >> 8, h = c >> 6, cc = c & 63;
;       const float gw = lng[c], gb = lnb[c];
.LBB0_170:
	global_load_dwordx4 v[12:15], v[8:9], off
	global_load_dwordx4 v[130:133], v[6:7], off
	global_load_dwordx4 v[134:137], v[4:5], off
	global_load_dwordx4 v[138:141], v[2:3], off
	v_add_u32_e32 v1, s2, v0
	v_and_b32_e32 v11, 0xfffffe0, v1
	v_lshl_add_u32 v11, v11, 4, v10
	s_addk_i32 s2, 0x800
	v_lshl_add_u64 v[8:9], v[8:9], 0, s[6:7]
	s_cmpk_eq_i32 s2, 0x2000
	s_waitcnt vmcnt(3)
	ds_write_b128 v11, v[12:15]
	v_add_u32_e32 v11, 0x200, v1
	v_and_b32_e32 v11, 0xfffffe0, v11
	v_lshl_add_u32 v11, v11, 4, v10
	v_lshl_add_u64 v[6:7], v[6:7], 0, s[6:7]
	s_waitcnt vmcnt(2)
	ds_write_b128 v11, v[130:133]
	v_add_u32_e32 v11, 0x400, v1
	v_and_b32_e32 v11, 0xfffffe0, v11
	v_lshl_add_u32 v11, v11, 4, v10
	v_add_u32_e32 v1, 0x600, v1
	v_and_b32_e32 v1, 0xfffffe0, v1
	v_lshl_add_u32 v1, v1, 4, v10
	v_lshl_add_u64 v[4:5], v[4:5], 0, s[6:7]
	s_waitcnt vmcnt(1)
	ds_write_b128 v11, v[134:137]
	v_lshl_add_u64 v[2:3], v[2:3], 0, s[6:7]
	s_waitcnt vmcnt(0)
	ds_write_b128 v1, v[138:141]
	s_cbranch_scc0 .LBB0_170
	v_readlane_b32 s2, v253, 22
	v_readlane_b32 s3, v253, 23
	s_andn2_b64 vcc, exec, s[2:3]
	s_waitcnt lgkmcnt(0)
	s_barrier
	s_cbranch_vccnz .LBB0_180
	s_add_u32 s16, s4, 0x2000000
	s_addc_u32 s17, s5, 0
	s_lshl_b32 s6, s55, 10
	s_add_u32 s18, s8, s6
	s_addc_u32 s19, s9, 0
	s_add_u32 s10, s10, s6
	s_addc_u32 s11, s11, 0
	s_add_u32 s2, s14, s6
	s_addc_u32 s3, s15, 0
	s_add_u32 s6, s12, s6
	v_and_b32_e32 v38, 0xff, v0
	s_addc_u32 s7, s13, 0
	v_bfe_u32 v39, v0, 6, 2
	v_lshlrev_b32_e32 v16, 2, v38
	v_lshl_add_u64 v[40:41], s[6:7], 0, v[16:17]
	v_lshl_add_u64 v[42:43], s[2:3], 0, v[16:17]
	v_lshlrev_b32_e32 v16, 2, v39
	v_bfe_u32 v6, v0, 4, 2
	v_lshl_add_u64 v[4:5], s[4:5], 0, v[16:17]
	s_mov_b64 s[2:3], 0x7600000
	v_lshlrev_b32_e32 v16, 1, v38
	v_lshl_add_u64 v[44:45], v[4:5], 0, s[2:3]
	v_lshl_add_u64 v[4:5], s[4:5], 0, v[16:17]
	s_mov_b64 s[2:3], 0x12000000
	v_lshlrev_b32_e32 v50, 4, v6
	v_mov_b32_e32 v51, v17
	v_and_b32_e32 v3, 15, v0
	v_ashrrev_i32_e32 v7, 2, v0
	v_lshl_add_u64 v[46:47], v[4:5], 0, s[2:3]
	v_lshl_add_u64 v[4:5], s[4:5], 0, v[50:51]
	s_mov_b64 s[2:3], 0x3000000
	v_lshrrev_b32_e32 v1, 4, v0
	v_and_b32_e32 v2, 63, v0
	v_lshlrev_b32_e32 v48, 3, v6
	v_lshl_add_u64 v[52:53], v[4:5], 0, s[2:3]
	v_bitop3_b32 v4, v6, v3, 4 bitop3:0x36
	v_bitop3_b32 v5, v6, v3, 8 bitop3:0x36
	v_bitop3_b32 v9, v6, v3, 12 bitop3:0x36
	v_bitop3_b32 v10, v6, v3, 16 bitop3:0x36
	v_bitop3_b32 v11, v6, v3, 20 bitop3:0x36
	v_bitop3_b32 v12, v6, v3, 24 bitop3:0x36
	v_bitop3_b32 v6, v6, v3, 28 bitop3:0x36
	v_bfi_b32 v73, -16, v7, v0
	v_lshlrev_b32_e32 v0, 9, v3
	v_lshl_or_b32 v6, v6, 4, v0
	v_add_u32_e32 v75, 16, v6
	v_lshl_or_b32 v6, v12, 4, v0
	v_add_u32_e32 v76, 16, v6
	v_lshl_or_b32 v6, v11, 4, v0
	v_bitop3_b32 v1, v1, v3, 3 bitop3:0x6c
	v_add_u32_e32 v77, 16, v6
	v_lshl_or_b32 v6, v10, 4, v0
	v_mov_b32_e32 v49, v17
	v_add_u32_e32 v78, 16, v6
	v_lshl_or_b32 v6, v9, 4, v0
	v_lshl_or_b32 v5, v5, 4, v0
	v_lshl_or_b32 v4, v4, 4, v0
	v_lshl_or_b32 v0, v1, 4, v0
	v_add_u32_e32 v82, 16, v0
	v_lshl_add_u64 v[0:1], s[4:5], 0, v[48:49]
	s_mov_b64 s[2:3], 0x3000024
	v_and_b32_e32 v14, 64, v239
	v_lshl_add_u64 v[54:55], v[0:1], 0, s[2:3]
	s_and_b32 s2, s24, 0xff
	v_xor_b32_e32 v13, 16, v239
	v_add_u32_e32 v14, 64, v14
	s_mul_hi_u32 s2, s2, 0x12492493
	v_cmp_lt_i32_e32 vcc, v13, v14
	s_lshl_b32 s2, s2, 10
	s_add_u32 s2, s8, s2
	v_cndmask_b32_e32 v13, v239, v13, vcc
	v_lshlrev_b32_e32 v71, 2, v13
	v_xor_b32_e32 v13, 32, v239
	s_addc_u32 s3, s9, 0
	v_cmp_lt_i32_e32 vcc, v13, v14
	v_lshl_add_u64 v[0:1], s[2:3], 0, v[50:51]
	s_mov_b64 s[2:3], 0x4c
	v_and_b32_e32 v70, 0xffffffc0, v7
	v_and_b32_e32 v8, -16, v7
	v_cndmask_b32_e32 v13, v239, v13, vcc
	v_readlane_b32 s6, v253, 54
	v_lshl_add_u64 v[58:59], v[0:1], 0, s[2:3]
	v_readlane_b32 s2, v254, 6
	v_lshlrev_b32_e32 v72, 2, v13
	v_add_u32_e32 v74, s6, v70
	v_add_u32_e32 v79, 16, v6
	v_add_u32_e32 v80, 16, v5
	v_add_u32_e32 v81, 16, v4
	v_add3_u32 v56, s6, v8, v3
	v_lshlrev_b32_e32 v16, 1, v2
	s_mov_b32 s8, s2
	v_readlane_b32 s3, v254, 7

; DI float bf2f(u16 h) { return __uint_as_float(((unsigned)h) << 16); }
; DI void phase_post(const PRef& p, int l) {
;     ...
;       for (int i0 = 0; i0 < 64; i0 += 8) {
;         float yv[8], vv[8], gq[8], bo[8];
; #pragma unroll
;         for (int u = 0; u < 8; ++u) {
;           const int tok = tk0 + half * 64 + i0 + u;
;           const int b = tok >> 12, t = tok & (SEQ - 1);
;           const char* rp = rec + ((size_t)((b * 4 + h) * SEQ + t)) * 1152;
;           yv[u] = Y[(size_t)tok * 256 + c];
;           vv[u] = bf2f(reinterpret_cast<const u16*>(rp + 1024)[cc]);
;           gq[u] = bf2f(gbuf[(size_t)tok * 256 + c]);
;           bo[u] = bonus[(size_t)tok * 4 + h];
;         }
.LBB0_174:
	v_add_u32_e32 v22, s3, v74
	v_mov_b64_e32 v[14:15], s[4:5]
	v_add_u32_e32 v28, 8, v22
	v_ashrrev_i32_e32 v29, 31, v28
	v_add_u32_e32 v0, 9, v22
	v_ashrrev_i32_e32 v1, 31, v0
	v_add_u32_e32 v8, 10, v22
	v_ashrrev_i32_e32 v9, 31, v8
	v_add_u32_e32 v2, 11, v22
	v_ashrrev_i32_e32 v3, 31, v2
	v_add_u32_e32 v10, 12, v22
	v_ashrrev_i32_e32 v11, 31, v10
	v_add_u32_e32 v4, 13, v22
	v_ashrrev_i32_e32 v5, 31, v4
	v_add_u32_e32 v12, 14, v22
	v_ashrrev_i32_e32 v13, 31, v12
	v_add_u32_e32 v6, 15, v22
	v_ashrrev_i32_e32 v7, 31, v6
	v_and_or_b32 v18, v28, s14, v34
	v_mad_i64_i32 v[130:131], s[6:7], v18, s52, v[14:15]
	v_lshl_add_u64 v[130:131], v[130:131], 0, v[16:17]
	v_add_co_u32_e32 v130, vcc, s53, v130
	v_lshlrev_b64 v[132:133], 8, v[28:29]
	v_or_b32_e32 v132, v132, v38
	v_addc_co_u32_e32 v131, vcc, 0, v131, vcc
	global_load_ushort v136, v[130:131], off offset:1024
	v_lshl_add_u64 v[134:135], v[132:133], 2, s[4:5]
	global_load_dword v35, v[134:135], off
	v_lshl_add_u64 v[134:135], v[132:133], 1, s[16:17]
	global_load_ushort v137, v[134:135], off
	v_lshl_add_u64 v[134:135], v[28:29], 4, v[44:45]
	global_load_dword v63, v[134:135], off
	v_and_or_b32 v18, v0, s15, v34
	v_mad_i64_i32 v[130:131], s[6:7], v18, s52, v[14:15]
	v_lshl_add_u64 v[130:131], v[130:131], 0, v[16:17]
	v_add_co_u32_e32 v130, vcc, s53, v130
	v_lshlrev_b64 v[132:133], 8, v[0:1]
	v_or_b32_e32 v132, v132, v38
	v_addc_co_u32_e32 v131, vcc, 0, v131, vcc
	global_load_ushort v138, v[130:131], off offset:1024
	v_lshl_add_u64 v[134:135], v[132:133], 2, s[4:5]
	global_load_dword v62, v[134:135], off
	v_lshl_add_u64 v[134:135], v[132:133], 1, s[16:17]
	global_load_ushort v139, v[134:135], off
	v_lshl_add_u64 v[134:135], v[0:1], 4, v[44:45]
	global_load_dword v90, v[134:135], off
	v_and_or_b32 v18, v8, s21, v34
	v_mad_i64_i32 v[130:131], s[6:7], v18, s52, v[14:15]
	v_lshl_add_u64 v[130:131], v[130:131], 0, v[16:17]
	v_add_co_u32_e32 v130, vcc, s53, v130
	v_lshlrev_b64 v[132:133], 8, v[8:9]
	v_or_b32_e32 v132, v132, v38
	v_addc_co_u32_e32 v131, vcc, 0, v131, vcc
	global_load_ushort v140, v[130:131], off offset:1024
	v_lshl_add_u64 v[134:135], v[132:133], 2, s[4:5]
	global_load_dword v37, v[134:135], off
	v_lshl_add_u64 v[134:135], v[132:133], 1, s[16:17]
	global_load_ushort v141, v[134:135], off
	v_lshl_add_u64 v[134:135], v[8:9], 4, v[44:45]
	global_load_dword v69, v[134:135], off
	v_and_or_b32 v18, v2, s22, v34
	v_mad_i64_i32 v[130:131], s[6:7], v18, s52, v[14:15]
	v_lshl_add_u64 v[130:131], v[130:131], 0, v[16:17]
	v_add_co_u32_e32 v130, vcc, s53, v130
	v_lshlrev_b64 v[132:133], 8, v[2:3]
	v_or_b32_e32 v132, v132, v38
	v_addc_co_u32_e32 v131, vcc, 0, v131, vcc
	global_load_ushort v142, v[130:131], off offset:1024
	v_lshl_add_u64 v[134:135], v[132:133], 2, s[4:5]
	global_load_dword v68, v[134:135], off
	v_lshl_add_u64 v[134:135], v[132:133], 1, s[16:17]
	global_load_ushort v143, v[134:135], off
	v_lshl_add_u64 v[134:135], v[2:3], 4, v[44:45]
	global_load_dword v95, v[134:135], off
	v_and_or_b32 v18, v10, s13, v34
	v_mad_i64_i32 v[130:131], s[6:7], v18, s52, v[14:15]
	v_lshl_add_u64 v[130:131], v[130:131], 0, v[16:17]
	v_add_co_u32_e32 v130, vcc, s53, v130
	v_lshlrev_b64 v[132:133], 8, v[10:11]
	v_or_b32_e32 v132, v132, v38
	v_addc_co_u32_e32 v131, vcc, 0, v131, vcc
	global_load_ushort v144, v[130:131], off offset:1024
	v_lshl_add_u64 v[134:135], v[132:133], 2, s[4:5]
	global_load_dword v61, v[134:135], off
	v_lshl_add_u64 v[134:135], v[132:133], 1, s[16:17]
	global_load_ushort v145, v[134:135], off
	v_lshl_add_u64 v[134:135], v[10:11], 4, v[44:45]
	global_load_dword v88, v[134:135], off
	v_and_or_b32 v18, v4, s23, v34
	v_mad_i64_i32 v[130:131], s[6:7], v18, s52, v[14:15]
	v_lshl_add_u64 v[130:131], v[130:131], 0, v[16:17]
	v_add_co_u32_e32 v130, vcc, s53, v130
	v_lshlrev_b64 v[132:133], 8, v[4:5]
	v_or_b32_e32 v132, v132, v38
	v_addc_co_u32_e32 v131, vcc, 0, v131, vcc
	global_load_ushort v146, v[130:131], off offset:1024
	v_lshl_add_u64 v[134:135], v[132:133], 2, s[4:5]
	global_load_dword v87, v[134:135], off
	v_lshl_add_u64 v[134:135], v[132:133], 1, s[16:17]
	global_load_ushort v147, v[134:135], off
	v_lshl_add_u64 v[134:135], v[4:5], 4, v[44:45]
	global_load_dword v98, v[134:135], off
	v_and_or_b32 v18, v12, s24, v34
	v_mad_i64_i32 v[130:131], s[6:7], v18, s52, v[14:15]
	v_lshl_add_u64 v[130:131], v[130:131], 0, v[16:17]
	v_add_co_u32_e32 v130, vcc, s53, v130
	v_lshlrev_b64 v[132:133], 8, v[12:13]
	v_or_b32_e32 v132, v132, v38
	v_addc_co_u32_e32 v131, vcc, 0, v131, vcc
	global_load_ushort v148, v[130:131], off offset:1024
	v_lshl_add_u64 v[134:135], v[132:133], 2, s[4:5]
	global_load_dword v66, v[134:135], off
	v_lshl_add_u64 v[134:135], v[132:133], 1, s[16:17]
	global_load_ushort v149, v[134:135], off
	v_lshl_add_u64 v[134:135], v[12:13], 4, v[44:45]
	global_load_dword v94, v[134:135], off
	v_and_or_b32 v18, v6, s48, v34
	v_mad_i64_i32 v[130:131], s[6:7], v18, s52, v[14:15]
	v_lshl_add_u64 v[130:131], v[130:131], 0, v[16:17]
	v_add_co_u32_e32 v130, vcc, s53, v130
	v_lshlrev_b64 v[132:133], 8, v[6:7]
	v_or_b32_e32 v132, v132, v38
	v_addc_co_u32_e32 v131, vcc, 0, v131, vcc
	global_load_ushort v150, v[130:131], off offset:1024
	v_lshl_add_u64 v[134:135], v[132:133], 2, s[4:5]
	global_load_dword v93, v[134:135], off
	v_lshl_add_u64 v[134:135], v[132:133], 1, s[16:17]
	global_load_ushort v151, v[134:135], off
	v_lshl_add_u64 v[134:135], v[6:7], 4, v[44:45]
	global_load_dword v100, v[134:135], off
	s_add_i32 s3, s3, 8
	s_cmp_gt_u32 s3, 55
	s_waitcnt vmcnt(0)
; DI float bf2f(u16 h) { return __uint_as_float(((unsigned)h) << 16); }
; DI void phase_post(const PRef& p, int l) {
;     ...
; #pragma unroll
;         for (int u = 0; u < 8; ++u) {
;           const int tok = tk0 + half * 64 + i0 + u;
;           const int b = tok >> 12, t = tok & (SEQ - 1);
;           const char* rp = rec + ((size_t)((b * 4 + h) * SEQ + t)) * 1152;
;           yv[u] = Y[(size_t)tok * 256 + c];
;           vv[u] = bf2f(reinterpret_cast<const u16*>(rp + 1024)[cc]);
;           gq[u] = bf2f(gbuf[(size_t)tok * 256 + c]);
;           bo[u] = bonus[(size_t)tok * 4 + h];
;         }
;         float mean[8], var[8];
; #pragma unroll
;         for (int u = 0; u < 8; ++u) { mean[u] = wave_sum(yv[u]) * (1.f / 64.f); }
; #pragma unroll
;         for (int u = 0; u < 8; ++u) { float d = yv[u] - mean[u]; var[u] = wave_sum(d * d) * (1.f / 64.f); }
	v_lshlrev_b32_e32 v36, 16, v136
	v_lshlrev_b32_e32 v57, 16, v137
	v_lshlrev_b32_e32 v67, 16, v138
	v_lshlrev_b32_e32 v84, 16, v139
	v_lshlrev_b32_e32 v60, 16, v140
	v_lshlrev_b32_e32 v64, 16, v141
	v_lshlrev_b32_e32 v86, 16, v142
	v_lshlrev_b32_e32 v91, 16, v143
	v_lshlrev_b32_e32 v65, 16, v144
	v_lshlrev_b32_e32 v83, 16, v145
	v_lshlrev_b32_e32 v92, 16, v146
	v_lshlrev_b32_e32 v96, 16, v147
	v_lshlrev_b32_e32 v85, 16, v148
	v_lshlrev_b32_e32 v89, 16, v149
	v_lshlrev_b32_e32 v97, 16, v150
	v_lshlrev_b32_e32 v99, 16, v151
	v_lshlrev_b64 v[28:29], 11, v[28:29]
	v_lshl_add_u64 v[28:29], v[46:47], 0, v[28:29]
	v_lshlrev_b64 v[0:1], 11, v[0:1]
	v_lshl_add_u64 v[0:1], v[46:47], 0, v[0:1]
	s_nop 0
	v_add_f32_dpp v14, v35, v35 quad_perm:[1,0,3,2] row_mask:0xf bank_mask:0xf bound_ctrl:1
	s_nop 1
	v_add_f32_dpp v14, v14, v14 quad_perm:[2,3,0,1] row_mask:0xf bank_mask:0xf bound_ctrl:1
	s_nop 1
	v_add_f32_dpp v14, v14, v14 row_half_mirror row_mask:0xf bank_mask:0xf bound_ctrl:1
	s_nop 1
	v_add_f32_dpp v14, v14, v14 row_mirror row_mask:0xf bank_mask:0xf bound_ctrl:1
	s_nop 0
	v_readlane_b32 s9, v14, 16
	v_readlane_b32 s12, v14, 48
	v_readlane_b32 s6, v14, 0
	v_readlane_b32 s7, v14, 32
	v_mov_b32_e32 v14, s9
	v_mov_b32_e32 v15, s12
	v_pk_add_f32 v[14:15], s[6:7], v[14:15]
	s_nop 0
	v_add_f32_e32 v18, v14, v15
	v_add_f32_dpp v14, v62, v62 quad_perm:[1,0,3,2] row_mask:0xf bank_mask:0xf bound_ctrl:1
	v_fmac_f32_e32 v35, 0xbc800000, v18
	s_nop 0
	v_add_f32_dpp v14, v14, v14 quad_perm:[2,3,0,1] row_mask:0xf bank_mask:0xf bound_ctrl:1
	s_nop 1
	v_add_f32_dpp v14, v14, v14 row_half_mirror row_mask:0xf bank_mask:0xf bound_ctrl:1
	s_nop 1
	v_add_f32_dpp v14, v14, v14 row_mirror row_mask:0xf bank_mask:0xf bound_ctrl:1
	s_nop 0
	v_readlane_b32 s9, v14, 16
	v_readlane_b32 s12, v14, 48
	v_readlane_b32 s6, v14, 0
	v_readlane_b32 s7, v14, 32
	v_mov_b32_e32 v14, s9
	v_mov_b32_e32 v15, s12
	v_pk_add_f32 v[14:15], s[6:7], v[14:15]
	s_nop 0
	v_add_f32_e32 v19, v14, v15
	v_add_f32_dpp v14, v37, v37 quad_perm:[1,0,3,2] row_mask:0xf bank_mask:0xf bound_ctrl:1
	v_fmac_f32_e32 v62, 0xbc800000, v19
	s_nop 0
	v_add_f32_dpp v14, v14, v14 quad_perm:[2,3,0,1] row_mask:0xf bank_mask:0xf bound_ctrl:1
	s_nop 1
	v_add_f32_dpp v14, v14, v14 row_half_mirror row_mask:0xf bank_mask:0xf bound_ctrl:1
	s_nop 1
	v_add_f32_dpp v14, v14, v14 row_mirror row_mask:0xf bank_mask:0xf bound_ctrl:1
	s_nop 0
	v_readlane_b32 s9, v14, 16
	v_readlane_b32 s12, v14, 48
	v_readlane_b32 s6, v14, 0
	v_readlane_b32 s7, v14, 32
	v_mov_b32_e32 v14, s9
	v_mov_b32_e32 v15, s12
	v_pk_add_f32 v[14:15], s[6:7], v[14:15]
	s_nop 0
	v_add_f32_e32 v20, v14, v15
	v_add_f32_dpp v14, v68, v68 quad_perm:[1,0,3,2] row_mask:0xf bank_mask:0xf bound_ctrl:1
	v_fmac_f32_e32 v37, 0xbc800000, v20
	s_nop 0
	v_add_f32_dpp v14, v14, v14 quad_perm:[2,3,0,1] row_mask:0xf bank_mask:0xf bound_ctrl:1
	s_nop 1
	v_add_f32_dpp v14, v14, v14 row_half_mirror row_mask:0xf bank_mask:0xf bound_ctrl:1
	s_nop 1
	v_add_f32_dpp v14, v14, v14 row_mirror row_mask:0xf bank_mask:0xf bound_ctrl:1
	s_nop 0
	v_readlane_b32 s9, v14, 16
	v_readlane_b32 s12, v14, 48
	v_readlane_b32 s6, v14, 0
	v_readlane_b32 s7, v14, 32
	v_mov_b32_e32 v14, s9
	v_mov_b32_e32 v15, s12
	v_pk_add_f32 v[14:15], s[6:7], v[14:15]
	s_nop 0
	v_add_f32_e32 v22, v14, v15
	v_add_f32_dpp v14, v61, v61 quad_perm:[1,0,3,2] row_mask:0xf bank_mask:0xf bound_ctrl:1
	v_fmac_f32_e32 v68, 0xbc800000, v22
	s_nop 0
	v_add_f32_dpp v14, v14, v14 quad_perm:[2,3,0,1] row_mask:0xf bank_mask:0xf bound_ctrl:1
	s_nop 1
	v_add_f32_dpp v14, v14, v14 row_half_mirror row_mask:0xf bank_mask:0xf bound_ctrl:1
	s_nop 1
	v_add_f32_dpp v14, v14, v14 row_mirror row_mask:0xf bank_mask:0xf bound_ctrl:1
	s_nop 0
	v_readlane_b32 s9, v14, 16
	v_readlane_b32 s12, v14, 48
	v_readlane_b32 s6, v14, 0
	v_readlane_b32 s7, v14, 32
	v_mov_b32_e32 v14, s9
	v_mov_b32_e32 v15, s12
	v_pk_add_f32 v[14:15], s[6:7], v[14:15]
	s_nop 0
	v_add_f32_e32 v23, v14, v15
	v_add_f32_dpp v14, v87, v87 quad_perm:[1,0,3,2] row_mask:0xf bank_mask:0xf bound_ctrl:1
	v_fmac_f32_e32 v61, 0xbc800000, v23
	s_nop 0
	v_add_f32_dpp v14, v14, v14 quad_perm:[2,3,0,1] row_mask:0xf bank_mask:0xf bound_ctrl:1
	s_nop 1
	v_add_f32_dpp v14, v14, v14 row_half_mirror row_mask:0xf bank_mask:0xf bound_ctrl:1
	s_nop 1
	v_add_f32_dpp v14, v14, v14 row_mirror row_mask:0xf bank_mask:0xf bound_ctrl:1
	s_nop 0
	v_readlane_b32 s9, v14, 16
	v_readlane_b32 s12, v14, 48
	v_readlane_b32 s6, v14, 0
	v_readlane_b32 s7, v14, 32
	v_mov_b32_e32 v14, s9
	v_mov_b32_e32 v15, s12
	v_pk_add_f32 v[14:15], s[6:7], v[14:15]
	s_nop 0
	v_add_f32_e32 v24, v14, v15
	v_add_f32_dpp v14, v66, v66 quad_perm:[1,0,3,2] row_mask:0xf bank_mask:0xf bound_ctrl:1
	v_fmac_f32_e32 v87, 0xbc800000, v24
	s_nop 0
	v_add_f32_dpp v14, v14, v14 quad_perm:[2,3,0,1] row_mask:0xf bank_mask:0xf bound_ctrl:1
	s_nop 1
	v_add_f32_dpp v14, v14, v14 row_half_mirror row_mask:0xf bank_mask:0xf bound_ctrl:1
	s_nop 1
	v_add_f32_dpp v14, v14, v14 row_mirror row_mask:0xf bank_mask:0xf bound_ctrl:1
	s_nop 0
	v_readlane_b32 s9, v14, 16
	v_readlane_b32 s12, v14, 48
	v_readlane_b32 s6, v14, 0
	v_readlane_b32 s7, v14, 32
	v_mov_b32_e32 v14, s9
	v_mov_b32_e32 v15, s12
	v_pk_add_f32 v[14:15], s[6:7], v[14:15]
	s_nop 0
	v_add_f32_e32 v101, v14, v15
	v_add_f32_dpp v14, v93, v93 quad_perm:[1,0,3,2] row_mask:0xf bank_mask:0xf bound_ctrl:1
	v_fmac_f32_e32 v66, 0xbc800000, v101
	s_nop 0
	v_add_f32_dpp v14, v14, v14 quad_perm:[2,3,0,1] row_mask:0xf bank_mask:0xf bound_ctrl:1
	s_nop 1
	v_add_f32_dpp v14, v14, v14 row_half_mirror row_mask:0xf bank_mask:0xf bound_ctrl:1
	s_nop 1
	v_add_f32_dpp v14, v14, v14 row_mirror row_mask:0xf bank_mask:0xf bound_ctrl:1
; DI void phase_post(const PRef& p, int l) {
;     ...
;         for (int u = 0; u < 8; ++u) { mean[u] = wave_sum(yv[u]) * (1.f / 64.f); }
; #pragma unroll
;         for (int u = 0; u < 8; ++u) { float d = yv[u] - mean[u]; var[u] = wave_sum(d * d) * (1.f / 64.f); }
	s_nop 0
	v_readlane_b32 s9, v14, 16
	v_readlane_b32 s12, v14, 48
	v_readlane_b32 s6, v14, 0
	v_readlane_b32 s7, v14, 32
	v_mov_b32_e32 v14, s9
	v_mov_b32_e32 v15, s12
	v_pk_add_f32 v[14:15], s[6:7], v[14:15]
	s_nop 0
	v_add_f32_e32 v104, v14, v15
	v_mul_f32_e32 v14, v35, v35
	v_fmac_f32_e32 v93, 0xbc800000, v104
	v_mul_f32_e32 v22, v93, v93
	v_mov_b32_dpp v14, v14 quad_perm:[1,0,3,2] row_mask:0xf bank_mask:0xf bound_ctrl:1
	v_fmac_f32_e32 v14, v35, v35
	v_mov_b32_dpp v22, v22 quad_perm:[1,0,3,2] row_mask:0xf bank_mask:0xf bound_ctrl:1
	v_fmac_f32_e32 v22, v93, v93
	v_add_f32_dpp v14, v14, v14 quad_perm:[2,3,0,1] row_mask:0xf bank_mask:0xf bound_ctrl:1
	s_nop 0
	v_add_f32_dpp v22, v22, v22 quad_perm:[2,3,0,1] row_mask:0xf bank_mask:0xf bound_ctrl:1
	v_add_f32_dpp v14, v14, v14 row_half_mirror row_mask:0xf bank_mask:0xf bound_ctrl:1
	s_nop 0
	v_add_f32_dpp v22, v22, v22 row_half_mirror row_mask:0xf bank_mask:0xf bound_ctrl:1
	v_add_f32_dpp v14, v14, v14 row_mirror row_mask:0xf bank_mask:0xf bound_ctrl:1
	s_nop 0
	v_readlane_b32 s9, v14, 16
	v_readlane_b32 s12, v14, 48
	v_readlane_b32 s6, v14, 0
	v_readlane_b32 s7, v14, 32
	v_mov_b32_e32 v14, s9
	v_mov_b32_e32 v15, s12
	v_pk_add_f32 v[30:31], s[6:7], v[14:15]
	v_mul_f32_e32 v14, v62, v62
	v_add_f32_dpp v22, v22, v22 row_mirror row_mask:0xf bank_mask:0xf bound_ctrl:1
	v_mov_b32_e32 v105, v30
	v_mov_b32_dpp v14, v14 quad_perm:[1,0,3,2] row_mask:0xf bank_mask:0xf bound_ctrl:1
	v_fmac_f32_e32 v14, v62, v62
	s_nop 1
	v_add_f32_dpp v14, v14, v14 quad_perm:[2,3,0,1] row_mask:0xf bank_mask:0xf bound_ctrl:1
	s_nop 1
	v_add_f32_dpp v14, v14, v14 row_half_mirror row_mask:0xf bank_mask:0xf bound_ctrl:1
	s_nop 1
	v_add_f32_dpp v14, v14, v14 row_mirror row_mask:0xf bank_mask:0xf bound_ctrl:1
	s_nop 0
	v_readlane_b32 s9, v14, 16
	v_readlane_b32 s12, v14, 48
	v_readlane_b32 s6, v14, 0
	v_readlane_b32 s7, v14, 32
	v_mov_b32_e32 v14, s9
	v_mov_b32_e32 v15, s12
	v_pk_add_f32 v[102:103], s[6:7], v[14:15]
	v_mul_f32_e32 v14, v37, v37
	v_mov_b32_e32 v104, v102
	v_mov_b32_e32 v30, v103
	v_mov_b32_dpp v14, v14 quad_perm:[1,0,3,2] row_mask:0xf bank_mask:0xf bound_ctrl:1
	v_fmac_f32_e32 v14, v37, v37
	v_pk_add_f32 v[30:31], v[104:105], v[30:31]
	s_nop 0
	v_add_f32_dpp v14, v14, v14 quad_perm:[2,3,0,1] row_mask:0xf bank_mask:0xf bound_ctrl:1
	s_nop 1
	v_add_f32_dpp v14, v14, v14 row_half_mirror row_mask:0xf bank_mask:0xf bound_ctrl:1
	s_nop 1
	v_add_f32_dpp v14, v14, v14 row_mirror row_mask:0xf bank_mask:0xf bound_ctrl:1
	s_nop 0
	v_readlane_b32 s9, v14, 16
	v_readlane_b32 s12, v14, 48
	v_readlane_b32 s6, v14, 0
	v_readlane_b32 s7, v14, 32
	v_mov_b32_e32 v14, s9
	v_mov_b32_e32 v15, s12
	v_pk_add_f32 v[20:21], s[6:7], v[14:15]
	v_mul_f32_e32 v14, v68, v68
	s_nop 1
	v_mov_b32_dpp v14, v14 quad_perm:[1,0,3,2] row_mask:0xf bank_mask:0xf bound_ctrl:1
	v_fmac_f32_e32 v14, v68, v68
	s_nop 1
	v_add_f32_dpp v14, v14, v14 quad_perm:[2,3,0,1] row_mask:0xf bank_mask:0xf bound_ctrl:1
	s_nop 1
	v_add_f32_dpp v14, v14, v14 row_half_mirror row_mask:0xf bank_mask:0xf bound_ctrl:1
	s_nop 1
	v_add_f32_dpp v14, v14, v14 row_mirror row_mask:0xf bank_mask:0xf bound_ctrl:1
	s_nop 0
	v_readlane_b32 s9, v14, 16
	v_readlane_b32 s12, v14, 48
	v_readlane_b32 s6, v14, 0
	v_readlane_b32 s7, v14, 32
	v_mov_b32_e32 v14, s9
	v_mov_b32_e32 v15, s12
	v_pk_add_f32 v[26:27], s[6:7], v[14:15]
	v_mul_f32_e32 v14, v61, v61
	s_nop 1
	v_mov_b32_dpp v14, v14 quad_perm:[1,0,3,2] row_mask:0xf bank_mask:0xf bound_ctrl:1
	v_fmac_f32_e32 v14, v61, v61
	s_nop 1
	v_add_f32_dpp v14, v14, v14 quad_perm:[2,3,0,1] row_mask:0xf bank_mask:0xf bound_ctrl:1
	s_nop 1
	v_add_f32_dpp v14, v14, v14 row_half_mirror row_mask:0xf bank_mask:0xf bound_ctrl:1
	s_nop 1
	v_add_f32_dpp v14, v14, v14 row_mirror row_mask:0xf bank_mask:0xf bound_ctrl:1
	s_nop 0
	v_readlane_b32 s9, v14, 16
	v_readlane_b32 s12, v14, 48
	v_readlane_b32 s6, v14, 0
	v_readlane_b32 s7, v14, 32
	v_mov_b32_e32 v14, s9
	v_mov_b32_e32 v15, s12
	v_pk_add_f32 v[18:19], s[6:7], v[14:15]
	v_mul_f32_e32 v14, v87, v87
	s_nop 1
	v_mov_b32_dpp v14, v14 quad_perm:[1,0,3,2] row_mask:0xf bank_mask:0xf bound_ctrl:1
	v_fmac_f32_e32 v14, v87, v87
	s_nop 1
	v_add_f32_dpp v14, v14, v14 quad_perm:[2,3,0,1] row_mask:0xf bank_mask:0xf bound_ctrl:1
	s_nop 1
	v_add_f32_dpp v14, v14, v14 row_half_mirror row_mask:0xf bank_mask:0xf bound_ctrl:1
	s_nop 1
	v_add_f32_dpp v14, v14, v14 row_mirror row_mask:0xf bank_mask:0xf bound_ctrl:1
	s_nop 0
	v_readlane_b32 s9, v14, 16
	v_readlane_b32 s12, v14, 48
	v_readlane_b32 s6, v14, 0
	v_readlane_b32 s7, v14, 32
	v_mov_b32_e32 v14, s9
	v_mov_b32_e32 v15, s12
	v_pk_add_f32 v[24:25], s[6:7], v[14:15]
	v_mul_f32_e32 v14, v66, v66
	s_nop 1
	v_mov_b32_dpp v14, v14 quad_perm:[1,0,3,2] row_mask:0xf bank_mask:0xf bound_ctrl:1
	v_fmac_f32_e32 v14, v66, v66
	s_nop 1
	v_add_f32_dpp v14, v14, v14 quad_perm:[2,3,0,1] row_mask:0xf bank_mask:0xf bound_ctrl:1
	s_nop 1
	v_add_f32_dpp v14, v14, v14 row_half_mirror row_mask:0xf bank_mask:0xf bound_ctrl:1
	s_nop 1
	v_add_f32_dpp v14, v14, v14 row_mirror row_mask:0xf bank_mask:0xf bound_ctrl:1
	s_nop 0
	v_readlane_b32 s9, v14, 16
	v_readlane_b32 s12, v14, 48
	v_readlane_b32 s6, v14, 0
	v_readlane_b32 s7, v14, 32
	v_mov_b32_e32 v14, s9
	v_mov_b32_e32 v15, s12
	v_readlane_b32 s9, v22, 16
	v_readlane_b32 s12, v22, 48
	v_pk_add_f32 v[14:15], s[6:7], v[14:15]
	v_readlane_b32 s6, v22, 0
	v_readlane_b32 s7, v22, 32
	v_mov_b32_e32 v22, s9
	v_mov_b32_e32 v23, s12
	v_pk_add_f32 v[22:23], s[6:7], v[22:23]
	s_mov_b32 s6, 0x3a27c5ac
	v_mov_b64_e32 v[102:103], s[6:7]
	v_pk_fma_f32 v[30:31], v[30:31], s[92:93], v[102:103] op_sel_hi:[1,0,0]
	s_nop 0
	v_mul_f32_e32 v101, 0x4b800000, v31
; DI u16 f2bf(float x) { return (u16)(pack2(x, 0.f) & 0xffffu); }
; DI void phase_post(const PRef& p, int l) {
;     ...
; #pragma unroll
;         for (int u = 0; u < 8; ++u) {
;           const int tok = tk0 + half * 64 + i0 + u;
;           float out = (yv[u] - mean[u]) * rsqrtf(var[u] + 64e-5f) * gw + gb + bo[u] * vv[u];
;           out *= gq[u];
;           hcat[(size_t)tok * 1024 + 512 + c] = f2bf(out);
;         }
;       }
;     }
;     {
;       const int tokw = tk0 + w * 16;
;       bf16x8 zf[8];
; #pragma unroll
;       for (int s = 0; s < 8; ++s) zf[s] = *reinterpret_cast<const bf16x8*>(Z + (size_t)(tokw + fr) * 256 + s * 32 + fq * 8);
	v_cmp_gt_f32_e64 s[6:7], s46, v31
	v_cmp_gt_f32_e32 vcc, s46, v30
	s_nop 0
	v_cndmask_b32_e64 v31, v31, v101, s[6:7]
	v_rsq_f32_e32 v31, v31
	s_nop 0
	v_mul_f32_e32 v101, 0x45800000, v31
	v_cndmask_b32_e64 v31, v31, v101, s[6:7]
	v_mul_f32_e32 v31, v35, v31
	v_fma_f32 v31, v32, v31, v33
	v_fmac_f32_e32 v31, v63, v36
	v_mul_f32_e32 v31, v31, v57
	v_cvt_pk_bf16_f32 v31, v31, s0
	global_store_short v[28:29], v31, off offset:1024
	v_mul_f32_e32 v28, 0x4b800000, v30
	v_cndmask_b32_e32 v28, v30, v28, vcc
	v_rsq_f32_e32 v28, v28
	s_nop 0
	v_mul_f32_e32 v29, 0x45800000, v28
	v_cndmask_b32_e32 v28, v28, v29, vcc
	v_mul_f32_e32 v28, v62, v28
	v_fma_f32 v28, v32, v28, v33
	v_fmac_f32_e32 v28, v90, v67
	v_mul_f32_e32 v28, v28, v84
	v_cvt_pk_bf16_f32 v28, v28, s0
	global_store_short v[0:1], v28, off offset:1024
	v_lshlrev_b64 v[0:1], 11, v[8:9]
	v_mov_b32_e32 v8, v26
	v_mov_b32_e32 v9, v20
	v_mov_b32_e32 v20, v27
	v_pk_add_f32 v[8:9], v[8:9], v[20:21]
	v_lshl_add_u64 v[0:1], v[46:47], 0, v[0:1]
	v_pk_fma_f32 v[8:9], v[8:9], s[92:93], v[102:103] op_sel_hi:[1,0,0]
	s_nop 0
	v_mul_f32_e32 v20, 0x4b800000, v9
	v_cmp_gt_f32_e64 s[6:7], s46, v9
	v_cmp_gt_f32_e32 vcc, s46, v8
	s_nop 0
	v_cndmask_b32_e64 v9, v9, v20, s[6:7]
	v_rsq_f32_e32 v9, v9
	s_nop 0
	v_mul_f32_e32 v20, 0x45800000, v9
	v_cndmask_b32_e64 v9, v9, v20, s[6:7]
	v_mul_f32_e32 v9, v37, v9
	v_fma_f32 v9, v32, v9, v33
	v_fmac_f32_e32 v9, v69, v60
	v_mul_f32_e32 v9, v9, v64
	v_cvt_pk_bf16_f32 v9, v9, s0
	global_store_short v[0:1], v9, off offset:1024
	v_mul_f32_e32 v0, 0x4b800000, v8
	v_cndmask_b32_e32 v0, v8, v0, vcc
	v_rsq_f32_e32 v0, v0
	s_nop 0
	v_mul_f32_e32 v1, 0x45800000, v0
	v_cndmask_b32_e32 v0, v0, v1, vcc
	v_mul_f32_e32 v0, v68, v0
	v_fma_f32 v0, v32, v0, v33
	v_fmac_f32_e32 v0, v95, v86
	v_mul_f32_e32 v0, v0, v91
	v_cvt_pk_bf16_f32 v8, v0, s0
	v_lshlrev_b64 v[0:1], 11, v[2:3]
	v_mov_b32_e32 v2, v24
	v_mov_b32_e32 v3, v18
	v_mov_b32_e32 v18, v25
	v_pk_add_f32 v[2:3], v[2:3], v[18:19]
	v_lshl_add_u64 v[0:1], v[46:47], 0, v[0:1]
	v_pk_fma_f32 v[2:3], v[2:3], s[92:93], v[102:103] op_sel_hi:[1,0,0]
	global_store_short v[0:1], v8, off offset:1024
	v_mul_f32_e32 v8, 0x4b800000, v3
	v_cmp_gt_f32_e64 s[6:7], s46, v3
	v_lshlrev_b64 v[0:1], 11, v[10:11]
	v_lshl_add_u64 v[0:1], v[46:47], 0, v[0:1]
	v_cndmask_b32_e64 v3, v3, v8, s[6:7]
	v_rsq_f32_e32 v3, v3
	v_cmp_gt_f32_e32 vcc, s46, v2
	v_mul_f32_e32 v8, 0x45800000, v3
	v_cndmask_b32_e64 v3, v3, v8, s[6:7]
	v_mul_f32_e32 v3, v61, v3
	v_fma_f32 v3, v32, v3, v33
	v_fmac_f32_e32 v3, v88, v65
	v_mul_f32_e32 v3, v3, v83
	v_cvt_pk_bf16_f32 v3, v3, s0
	global_store_short v[0:1], v3, off offset:1024
	v_mul_f32_e32 v0, 0x4b800000, v2
	v_cndmask_b32_e32 v0, v2, v0, vcc
	v_rsq_f32_e32 v0, v0
	v_mov_b32_e32 v3, v14
	v_mov_b32_e32 v14, v23
	v_mul_f32_e32 v1, 0x45800000, v0
	v_cndmask_b32_e32 v0, v0, v1, vcc
	v_mul_f32_e32 v0, v87, v0
	v_fma_f32 v0, v32, v0, v33
	v_fmac_f32_e32 v0, v98, v92
	v_mul_f32_e32 v0, v0, v96
	v_cvt_pk_bf16_f32 v2, v0, s0
	v_lshlrev_b64 v[0:1], 11, v[4:5]
	v_lshl_add_u64 v[0:1], v[46:47], 0, v[0:1]
	global_store_short v[0:1], v2, off offset:1024
	v_mov_b32_e32 v2, v22
	v_pk_add_f32 v[2:3], v[2:3], v[14:15]
	v_lshlrev_b64 v[0:1], 11, v[12:13]
	v_pk_fma_f32 v[2:3], v[2:3], s[92:93], v[102:103] op_sel_hi:[1,0,0]
	v_lshl_add_u64 v[0:1], v[46:47], 0, v[0:1]
	v_mul_f32_e32 v4, 0x4b800000, v3
	v_cmp_gt_f32_e64 s[6:7], s46, v3
	v_cmp_gt_f32_e32 vcc, s46, v2
	s_nop 0
	v_cndmask_b32_e64 v3, v3, v4, s[6:7]
	v_rsq_f32_e32 v3, v3
	s_nop 0
	v_mul_f32_e32 v4, 0x45800000, v3
	v_cndmask_b32_e64 v3, v3, v4, s[6:7]
	v_mul_f32_e32 v3, v66, v3
	v_fma_f32 v3, v32, v3, v33
	v_fmac_f32_e32 v3, v94, v85
	v_mul_f32_e32 v3, v3, v89
	v_cvt_pk_bf16_f32 v3, v3, s0
	global_store_short v[0:1], v3, off offset:1024
	v_mul_f32_e32 v0, 0x4b800000, v2
	v_cndmask_b32_e32 v0, v2, v0, vcc
	v_rsq_f32_e32 v0, v0
	s_nop 0
	v_mul_f32_e32 v1, 0x45800000, v0
	v_cndmask_b32_e32 v0, v0, v1, vcc
	v_mul_f32_e32 v0, v93, v0
	v_fma_f32 v0, v32, v0, v33
	s_waitcnt vmcnt(7)
	v_fmac_f32_e32 v0, v100, v97
	v_mul_f32_e32 v0, v0, v99
	v_cvt_pk_bf16_f32 v2, v0, s0
	v_lshlrev_b64 v[0:1], 11, v[6:7]
	v_lshl_add_u64 v[0:1], v[46:47], 0, v[0:1]
	global_store_short v[0:1], v2, off offset:1024
	s_cbranch_scc0 .LBB0_174
	v_add_u32_e32 v0, s2, v73
	v_ashrrev_i32_e32 v1, 31, v0
	v_lshlrev_b64 v[0:1], 9, v[0:1]
	v_lshl_add_u64 v[30:31], v[52:53], 0, v[0:1]
	global_load_dwordx4 v[0:3], v[30:31], off
	global_load_dwordx4 v[4:7], v[30:31], off offset:64
	global_load_dwordx4 v[8:11], v[30:31], off offset:128
	global_load_dwordx4 v[12:15], v[30:31], off offset:192
	global_load_dwordx4 v[18:21], v[30:31], off offset:256
	global_load_dwordx4 v[22:25], v[30:31], off offset:320
	global_load_dwordx4 v[26:29], v[30:31], off offset:384
	s_nop 0
	global_load_dwordx4 v[30:33], v[30:31], off offset:448
	v_ashrrev_i32_e32 v57, 31, v56
	v_lshlrev_b64 v[60:61], 9, v[56:57]
	v_lshl_add_u64 v[62:63], v[54:55], 0, v[60:61]
	v_mov_b32_e32 v34, 0
	s_mov_b32 s2, 0
	v_mov_b64_e32 v[64:65], v[58:59]
	s_mov_b32 s14, 0x12000000
; DI float sigmoidf_(float x) { return 1.f / (1.f + __expf(-x)); }
; DI void phase_post(const PRef& p, int l) {
;     ...
;         for (int nb = 0; nb < 16; ++nb) {
;           f32x4 acc = f32x4{0.f, 0.f, 0.f, 0.f};
; #pragma unroll
;           for (int s = 0; s < 8; ++s) {
;             bf16x8 wf = *reinterpret_cast<const bf16x8*>(shm + ((nb * 16 + fr) * 32 + ((s * 4 + fq) ^ fr)) * 8);
;             acc = __builtin_amdgcn_mfma_f32_16x16x32_bf16(wf, zf[s], acc, 0, 0, 0);
;           }
;           const int col = nb * 16 + fq * 4;
;           uint2 zr = *reinterpret_cast<const uint2*>(Z + (size_t)(tokw + fr) * 256 + col);
;           float z0 = __uint_as_float(zr.x << 16), z1 = __uint_as_float(zr.x & 0xffff0000u);
;           float z2 = __uint_as_float(zr.y << 16), z3 = __uint_as_float(zr.y & 0xffff0000u);
;           float o0 = z0 * sigmoidf_(acc[0] + glub[col]), o1 = z1 * sigmoidf_(acc[1] + glub[col + 1]);
;           float o2 = z2 * sigmoidf_(acc[2] + glub[col + 2]), o3 = z3 * sigmoidf_(acc[3] + glub[col + 3]);
;           if (pass == 0) ss += o0 * o0 + o1 * o1 + o2 * o2 + o3 * o3;
.LBB0_176:
	v_add_u32_e32 v35, s2, v82
	global_load_dwordx2 v[88:89], v[62:63], off offset:-36
	global_load_dwordx4 v[130:133], v[64:65], off offset:-76
	ds_read_b128 v[66:69], v35
	v_add_u32_e32 v83, s2, v81
	ds_read_b128 v[84:87], v83
	v_add_u32_e32 v92, s2, v80
	v_add_u32_e32 v93, s2, v79
	v_add_u32_e32 v94, s2, v78
	v_add_u32_e32 v95, s2, v77
	v_add_u32_e32 v96, s2, v76
	v_add_u32_e32 v97, s2, v75
	s_waitcnt vmcnt(7) lgkmcnt(1)
	v_mfma_f32_16x16x32_bf16 v[66:69], v[66:69], v[0:3], 0
	s_addk_i32 s2, 0x4000
	s_cmp_lg_u32 s2, 0x20000
	s_waitcnt vmcnt(7) lgkmcnt(0)
	v_mfma_f32_16x16x32_bf16 v[66:69], v[84:87], v[4:7], v[66:69]
	ds_read_b128 v[84:87], v92
	s_waitcnt vmcnt(2)
	s_waitcnt lgkmcnt(0)
	v_mfma_f32_16x16x32_bf16 v[66:69], v[84:87], v[8:11], v[66:69]
	ds_read_b128 v[84:87], v93
	s_waitcnt lgkmcnt(0)
	v_mfma_f32_16x16x32_bf16 v[66:69], v[84:87], v[12:15], v[66:69]
	ds_read_b128 v[84:87], v94
	s_waitcnt lgkmcnt(0)
	v_mfma_f32_16x16x32_bf16 v[66:69], v[84:87], v[18:21], v[66:69]
	ds_read_b128 v[84:87], v95
	s_waitcnt lgkmcnt(0)
	v_mfma_f32_16x16x32_bf16 v[66:69], v[84:87], v[22:25], v[66:69]
	ds_read_b128 v[84:87], v96
	s_waitcnt lgkmcnt(0)
	v_mfma_f32_16x16x32_bf16 v[66:69], v[84:87], v[26:29], v[66:69]
	ds_read_b128 v[84:87], v97
	s_waitcnt lgkmcnt(0)
	v_mfma_f32_16x16x32_bf16 v[66:69], v[84:87], v[30:33], v[66:69]
	s_waitcnt vmcnt(0)
	s_nop 5
	v_and_b32_e32 v90, 0xffff0000, v89
	v_lshlrev_b32_e32 v91, 16, v89
	v_add_f32_e32 v67, v67, v131
	v_add_f32_e32 v66, v66, v130
	v_mul_f32_e32 v67, 0xbfb8aa3b, v67
	v_mul_f32_e32 v66, 0xbfb8aa3b, v66
	v_add_f32_e32 v36, v69, v133
	v_add_f32_e32 v37, v68, v132
	v_exp_f32_e32 v68, v67
	v_exp_f32_e32 v69, v66
	v_and_b32_e32 v86, 0xffff0000, v88
	v_lshlrev_b32_e32 v87, 16, v88
	v_mul_f32_e32 v36, 0xbfb8aa3b, v36
	v_pk_add_f32 v[66:67], v[68:69], 1.0 op_sel_hi:[1,0]
	v_mul_f32_e32 v37, 0xbfb8aa3b, v37
	v_div_scale_f32 v68, s[6:7], v67, v67, 1.0
	v_rcp_f32_e32 v69, v68
	v_exp_f32_e32 v36, v36
	v_exp_f32_e32 v37, v37
	v_fma_f32 v84, -v68, v69, 1.0
	v_fmac_f32_e32 v69, v84, v69
	v_div_scale_f32 v84, vcc, 1.0, v67, 1.0
	v_mul_f32_e32 v85, v84, v69
	v_fma_f32 v88, -v68, v85, v84
	v_fmac_f32_e32 v85, v88, v69
	v_fma_f32 v68, -v68, v85, v84
	v_div_fmas_f32 v68, v68, v69, v85
	v_div_fixup_f32 v67, v68, v67, 1.0
	v_div_scale_f32 v68, s[6:7], v66, v66, 1.0
	v_rcp_f32_e32 v69, v68
	v_pk_add_f32 v[36:37], v[36:37], 1.0 op_sel_hi:[1,0]
	v_fma_f32 v84, -v68, v69, 1.0
	v_fmac_f32_e32 v69, v84, v69
	v_div_scale_f32 v84, vcc, 1.0, v66, 1.0
	v_mul_f32_e32 v85, v84, v69
	v_fma_f32 v88, -v68, v85, v84
	v_fmac_f32_e32 v85, v88, v69
	v_fma_f32 v68, -v68, v85, v84
	v_div_fmas_f32 v68, v68, v69, v85
	v_div_fixup_f32 v66, v68, v66, 1.0
	v_div_scale_f32 v68, s[6:7], v37, v37, 1.0
	v_rcp_f32_e32 v69, v68
	v_pk_mul_f32 v[66:67], v[66:67], v[86:87]
	v_fma_f32 v84, -v68, v69, 1.0
	v_fmac_f32_e32 v69, v84, v69
	v_div_scale_f32 v84, vcc, 1.0, v37, 1.0
	v_mul_f32_e32 v85, v84, v69
	v_fma_f32 v86, -v68, v85, v84
	v_fmac_f32_e32 v85, v86, v69
	v_fma_f32 v68, -v68, v85, v84
	v_div_fmas_f32 v68, v68, v69, v85
	v_div_fixup_f32 v37, v68, v37, 1.0
	v_div_scale_f32 v68, s[6:7], v36, v36, 1.0
	v_rcp_f32_e32 v69, v68
	v_pk_mul_f32 v[66:67], v[66:67], v[66:67]
	v_fma_f32 v84, -v68, v69, 1.0
	v_fmac_f32_e32 v69, v84, v69
	v_div_scale_f32 v84, vcc, 1.0, v36, 1.0
	v_mul_f32_e32 v85, v84, v69
	v_fma_f32 v86, -v68, v85, v84
	v_fmac_f32_e32 v85, v86, v69
	v_fma_f32 v68, -v68, v85, v84
	v_div_fmas_f32 v68, v68, v69, v85
	v_div_fixup_f32 v36, v68, v36, 1.0
	v_pk_mul_f32 v[36:37], v[36:37], v[90:91]
	v_add_f32_e32 v66, v66, v67
	v_pk_mul_f32 v[36:37], v[36:37], v[36:37]
	global_load_dwordx2 v[86:87], v[62:63], off offset:-4
	global_load_dwordx4 v[134:137], v[64:65], off offset:-12
	v_add_f32_e32 v37, v37, v66
	v_add_f32_e32 v36, v36, v37
	v_add_f32_e32 v90, v34, v36
	ds_read_b128 v[34:37], v35 offset:8192
	ds_read_b128 v[66:69], v83 offset:8192
	s_waitcnt lgkmcnt(1)
	v_mfma_f32_16x16x32_bf16 v[34:37], v[34:37], v[0:3], 0
	v_lshl_add_u64 v[62:63], v[62:63], 0, 64
	s_waitcnt lgkmcnt(0)
; DI unsigned pack2(float a, float b) { f32v2 v = {a, b}; return __builtin_bit_cast(unsigned, __builtin_convertvector(v, bf16v2)); }
; DI float sigmoidf_(float x) { return 1.f / (1.f + __expf(-x)); }
; DI void phase_post(const PRef& p, int l) {
;     ...
;         for (int nb = 0; nb < 16; ++nb) {
;           f32x4 acc = f32x4{0.f, 0.f, 0.f, 0.f};
; #pragma unroll
;           for (int s = 0; s < 8; ++s) {
;             bf16x8 wf = *reinterpret_cast<const bf16x8*>(shm + ((nb * 16 + fr) * 32 + ((s * 4 + fq) ^ fr)) * 8);
;             acc = __builtin_amdgcn_mfma_f32_16x16x32_bf16(wf, zf[s], acc, 0, 0, 0);
;           }
;           const int col = nb * 16 + fq * 4;
;           uint2 zr = *reinterpret_cast<const uint2*>(Z + (size_t)(tokw + fr) * 256 + col);
;           float z0 = __uint_as_float(zr.x << 16), z1 = __uint_as_float(zr.x & 0xffff0000u);
;           float z2 = __uint_as_float(zr.y << 16), z3 = __uint_as_float(zr.y & 0xffff0000u);
;           float o0 = z0 * sigmoidf_(acc[0] + glub[col]), o1 = z1 * sigmoidf_(acc[1] + glub[col + 1]);
;           float o2 = z2 * sigmoidf_(acc[2] + glub[col + 2]), o3 = z3 * sigmoidf_(acc[3] + glub[col + 3]);
;           if (pass == 0) ss += o0 * o0 + o1 * o1 + o2 * o2 + o3 * o3;
;           else {
;             uint2 ov;
;             ov.x = pack2(o0 * rms * outg[col], o1 * rms * outg[col + 1]);
;             ov.y = pack2(o2 * rms * outg[col + 2], o3 * rms * outg[col + 3]);
;             *reinterpret_cast<uint2*>(hcat + (size_t)(tokw + fr) * 1024 + 768 + col) = ov;
;           }
;         }
;         if (pass == 0) { ss += __shfl_xor(ss, 16); ss += __shfl_xor(ss, 32); rms = rsqrtf(ss * (1.f / 256.f) + 1e-6f); }
	v_mfma_f32_16x16x32_bf16 v[34:37], v[66:69], v[4:7], v[34:37]
	ds_read_b128 v[66:69], v92 offset:8192
	s_waitcnt lgkmcnt(0)
	v_mfma_f32_16x16x32_bf16 v[34:37], v[66:69], v[8:11], v[34:37]
	ds_read_b128 v[66:69], v93 offset:8192
	s_waitcnt lgkmcnt(0)
	v_mfma_f32_16x16x32_bf16 v[34:37], v[66:69], v[12:15], v[34:37]
	ds_read_b128 v[66:69], v94 offset:8192
	s_waitcnt lgkmcnt(0)
	v_mfma_f32_16x16x32_bf16 v[34:37], v[66:69], v[18:21], v[34:37]
	ds_read_b128 v[66:69], v95 offset:8192
	s_waitcnt lgkmcnt(0)
	v_mfma_f32_16x16x32_bf16 v[34:37], v[66:69], v[22:25], v[34:37]
	ds_read_b128 v[66:69], v96 offset:8192
	s_waitcnt lgkmcnt(0)
	v_mfma_f32_16x16x32_bf16 v[34:37], v[66:69], v[26:29], v[34:37]
	ds_read_b128 v[66:69], v97 offset:8192
	s_waitcnt lgkmcnt(0)
	v_mfma_f32_16x16x32_bf16 v[34:37], v[66:69], v[30:33], v[34:37]
	v_lshl_add_u64 v[64:65], v[64:65], 0, s[82:83]
	s_waitcnt vmcnt(0)
	s_nop 4
	v_and_b32_e32 v88, 0xffff0000, v87
	v_lshlrev_b32_e32 v89, 16, v87
	v_add_f32_e32 v37, v37, v137
	v_add_f32_e32 v36, v36, v136
	v_add_f32_e32 v35, v35, v135
	v_add_f32_e32 v34, v34, v134
	v_mul_f32_e32 v37, 0xbfb8aa3b, v37
	v_mul_f32_e32 v36, 0xbfb8aa3b, v36
	v_mul_f32_e32 v35, 0xbfb8aa3b, v35
	v_mul_f32_e32 v34, 0xbfb8aa3b, v34
	v_exp_f32_e32 v84, v37
	v_exp_f32_e32 v85, v36
	v_exp_f32_e32 v36, v35
	v_exp_f32_e32 v37, v34
	v_and_b32_e32 v68, 0xffff0000, v86
	v_lshlrev_b32_e32 v69, 16, v86
	v_pk_add_f32 v[34:35], v[36:37], 1.0 op_sel_hi:[1,0]
	s_nop 0
	v_div_scale_f32 v36, s[6:7], v35, v35, 1.0
	v_rcp_f32_e32 v37, v36
	s_nop 0
	v_fma_f32 v66, -v36, v37, 1.0
	v_fmac_f32_e32 v37, v66, v37
	v_div_scale_f32 v66, vcc, 1.0, v35, 1.0
	v_mul_f32_e32 v67, v66, v37
	v_fma_f32 v83, -v36, v67, v66
	v_fmac_f32_e32 v67, v83, v37
	v_fma_f32 v36, -v36, v67, v66
	v_div_fmas_f32 v36, v36, v37, v67
	v_div_fixup_f32 v35, v36, v35, 1.0
	v_div_scale_f32 v36, s[6:7], v34, v34, 1.0
	v_rcp_f32_e32 v37, v36
	s_nop 0
	v_fma_f32 v66, -v36, v37, 1.0
	v_fmac_f32_e32 v37, v66, v37
	v_div_scale_f32 v66, vcc, 1.0, v34, 1.0
	v_mul_f32_e32 v67, v66, v37
	v_fma_f32 v83, -v36, v67, v66
	v_fmac_f32_e32 v67, v83, v37
	v_fma_f32 v36, -v36, v67, v66
	v_div_fmas_f32 v36, v36, v37, v67
	v_div_fixup_f32 v34, v36, v34, 1.0
	v_pk_add_f32 v[36:37], v[84:85], 1.0 op_sel_hi:[1,0]
	v_pk_mul_f32 v[34:35], v[34:35], v[68:69]
	v_div_scale_f32 v66, s[6:7], v37, v37, 1.0
	v_rcp_f32_e32 v67, v66
	v_pk_mul_f32 v[34:35], v[34:35], v[34:35]
	v_fma_f32 v68, -v66, v67, 1.0
	v_fmac_f32_e32 v67, v68, v67
	v_div_scale_f32 v68, vcc, 1.0, v37, 1.0
	v_mul_f32_e32 v69, v68, v67
	v_fma_f32 v83, -v66, v69, v68
	v_fmac_f32_e32 v69, v83, v67
	v_fma_f32 v66, -v66, v69, v68
	v_div_fmas_f32 v66, v66, v67, v69
	v_div_fixup_f32 v37, v66, v37, 1.0
	v_div_scale_f32 v66, s[6:7], v36, v36, 1.0
	v_rcp_f32_e32 v67, v66
	v_add_f32_e32 v34, v34, v35
	v_fma_f32 v68, -v66, v67, 1.0
	v_fmac_f32_e32 v67, v68, v67
	v_div_scale_f32 v68, vcc, 1.0, v36, 1.0
	v_mul_f32_e32 v69, v68, v67
	v_fma_f32 v83, -v66, v69, v68
	v_fmac_f32_e32 v69, v83, v67
	v_fma_f32 v66, -v66, v69, v68
	v_div_fmas_f32 v66, v66, v67, v69
	v_div_fixup_f32 v36, v66, v36, 1.0
	v_pk_mul_f32 v[36:37], v[36:37], v[88:89]
	s_nop 0
	v_pk_mul_f32 v[36:37], v[36:37], v[36:37]
	s_nop 0
	v_add_f32_e32 v34, v37, v34
	v_add_f32_e32 v34, v36, v34
	v_add_f32_e32 v34, v90, v34
	s_cbranch_scc1 .LBB0_176
	ds_bpermute_b32 v35, v71, v34
	v_lshlrev_b64 v[36:37], 11, v[56:57]
	s_mov_b32 s9, 0
	s_mov_b64 s[2:3], s[10:11]
	v_lshl_add_u64 v[36:37], s[4:5], 0, v[36:37]
	s_waitcnt lgkmcnt(0)
	v_add_f32_e32 v62, v34, v35
	ds_bpermute_b32 v63, v72, v62
	v_lshl_add_u64 v[34:35], s[4:5], 0, v[60:61]
	s_mov_b64 s[6:7], s[18:19]
	s_waitcnt lgkmcnt(0)
	v_add_f32_e32 v57, v62, v63
	v_fmamk_f32 v57, v57, 0x3b800000, v241
	v_mul_f32_e32 v60, 0x4b800000, v57
	v_cmp_gt_f32_e32 vcc, s46, v57
	s_nop 1
	v_cndmask_b32_e32 v57, v57, v60, vcc
	v_rsq_f32_e32 v57, v57
	s_nop 0
	v_mul_f32_e32 v60, 0x45800000, v57
	v_cndmask_b32_e32 v60, v57, v60, vcc
	v_mov_b32_e32 v61, v60
